# v78 plus retention S-section first four fragment reads issued right after barrier 1 (before the GroupNorm statistics reduction)
# speedup vs baseline: 1.0081x; 1.0081x over previous
; #define LAS __attribute__((address_space(3)))
; #define LBAR() do { asm volatile("s_waitcnt lgkmcnt(0)" ::: "memory"); __builtin_amdgcn_s_barrier(); asm volatile("" ::: "memory"); } while (0)
; __device__ __forceinline__ void retention_unit(LAS unsigned char* lds, const Ptrs& P, int b, int h, int tid) {
;     ...
;         if (n < 32) {
; #pragma unroll
;             for (int j2 = 0; j2 < 2; ++j2) {
;                 const int jt = (w & 1) * 2 + j2; f32x4 a4 = (f32x4){0.f, 0.f, 0.f, 0.f};
; #pragma unroll
;                 for (int ks = 0; ks < 2; ++ks) {
;                     const bf16x8 qf = *(const LAS bf16x8*)(Qs + (16 * it3 + fr) * S72 + 32 * ks + 8 * fq), kf = *(const LAS bf16x8*)(Ks + (16 * jt + fr) * S72 + 32 * ks + 8 * fq);
;                     a4 = mfma16(kf, qf, a4); }
;                 a4 = a4 * decv[j2];
;                 v2u pw; pw.x = pk2(a4[0], a4[1]); pw.y = pk2(a4[2], a4[3]);
;                 *(LAS v2u*)(Ss + (16 * it3 + fr) * S72 + 16 * jt + 4 * fq) = pw;
;             }
;         }
;         LBAR();
;         if (n >= 1) {
; #pragma unroll
;             for (int it = 0; it < 4; ++it) { const int i = 16 * it + fr; const float mean = stat[i * 2], rstd = stat[i * 2 + 1]; const v2u sg = sgr[it];
;                 const f32x4 y = (op[it] - mean) * rstd * gng4 * (f32x4){bflo(sg.x), bfhi(sg.x), bflo(sg.y), bfhi(sg.y)};
;                 v2u pw; pw.x = pk2(y[0], y[1]); pw.y = pk2(y[2], y[3]);
;                 *(v2u*)(gol + ((size_t)(n - 1) * 64 + 16 * it) * 1024) = pw; }
;         }
;         if (n < 32) {
;             f32x4 o[4]; bf16x8 bst[2], bv[2];
; #pragma unroll
;             for (int ks = 0; ks < 2; ++ks) { bst[ks] = *(const LAS bf16x8*)(St + (16 * w + fr) * S72 + 32 * ks + 8 * fq); bv[ks] = tr_frag(bufc + ROFF_V, S144 * 2, w, ks, fq, fr); }
; #pragma unroll
;             for (int it = 0; it < 4; ++it) { o[it] = (f32x4){0.f, 0.f, 0.f, 0.f};
; #pragma unroll
;                 for (int ks = 0; ks < 2; ++ks) { const bf16x8 qf = *(const LAS bf16x8*)(Qs + (16 * it + fr) * S72 + 32 * ks + 8 * fq); o[it] = mfma16(bst[ks], qf, o[it]); }
;                 o[it] = o[it] * dqv[it];
; #pragma unroll
;                 for (int ks = 0; ks < 2; ++ks) { const bf16x8 sf = *(const LAS bf16x8*)(Ss + (16 * it + fr) * S72 + 32 * ks + 8 * fq); o[it] = mfma16(bv[ks], sf, o[it]); }
;             }
.LBB0_657:
	s_or_b64 exec, exec, s[18:19]
	v_lshl_add_u32 v60, v155, 1, s90
	s_waitcnt lgkmcnt(0)
	v_add_u32_e32 v60, v60, v178
	s_waitcnt vmcnt(7)
	v_and_b32_e32 v61, 0xffff0000, v54
	v_add_u32_e32 v75, 0, v160
	v_add_u32_e32 v143, 0x21400, v75
	v_lshl_add_u64 v[120:121], s[26:27], 0, v[114:115]
	v_add3_u32 v204, s90, v82, v169
	s_waitcnt lgkmcnt(1)
	v_mfma_f32_16x16x32_bf16 v[56:59], v[216:219], v[188:191], 0
	s_add_i32 s18, s90, s87
	s_waitcnt vmcnt(5)
	v_lshlrev_b32_e32 v200, 16, v122
	v_and_b32_e32 v201, 0xffff0000, v122
	s_waitcnt lgkmcnt(0)
	v_mfma_f32_16x16x32_bf16 v[56:59], v[220:223], v[192:195], v[56:59]
	v_lshlrev_b32_e32 v122, 16, v123
	v_and_b32_e32 v123, 0xffff0000, v123
	v_add3_u32 v212, s90, v162, v170
	v_mov_b32_e32 v75, v74
	v_pk_mul_f32 v[18:19], v[74:75], v[18:19]
	s_nop 2
	v_pk_mul_f32 v[58:59], v[100:101], v[58:59]
	v_pk_mul_f32 v[56:57], v[98:99], v[56:57]
	v_pk_mul_f32 v[16:17], v[76:77], v[16:17]
	v_cvt_pk_bf16_f32 v56, v56, v57
	v_cvt_pk_bf16_f32 v57, v58, v59
	ds_write_b64 v177, v[56:57]
	ds_read_b128 v[56:59], v60 offset:9216
	ds_read_b128 v[184:187], v60 offset:9280
	ds_read_b128 v[216:219], v204
	ds_read_b128 v[220:223], v204 offset:64
	ds_read_b128 v[224:227], v204 offset:2304
	ds_read_b128 v[228:231], v204 offset:2368
	ds_read_b128 v[232:235], v204 offset:4608
	ds_read_b128 v[236:239], v204 offset:4672
	ds_read_b128 v[240:243], v204 offset:6912
	ds_read_b128 v[244:247], v204 offset:6976
	s_waitcnt lgkmcnt(9)
	v_mfma_f32_16x16x32_bf16 v[56:59], v[56:59], v[188:191], 0
	v_lshlrev_b32_e32 v60, 16, v54
	v_lshlrev_b32_e32 v188, 16, v55
	v_and_b32_e32 v189, 0xffff0000, v55
	s_waitcnt lgkmcnt(8)
	v_mfma_f32_16x16x32_bf16 v[54:57], v[184:187], v[192:195], v[56:59]
	v_mul_f32_e64 v14, v74, v14
	v_mul_f32_e64 v15, v75, v15
	v_pk_mul_f32 v[12:13], v[76:77], v[12:13]
	v_pk_mul_f32 v[10:11], v[74:75], v[10:11]
	v_add_co_u32_e32 v58, vcc, s66, v120
	v_pk_mul_f32 v[8:9], v[76:77], v[8:9]
	s_nop 1
	v_pk_mul_f32 v[56:57], v[94:95], v[56:57]
	v_pk_mul_f32 v[54:55], v[92:93], v[54:55]
	v_addc_co_u32_e32 v59, vcc, 0, v121, vcc
	v_cvt_pk_bf16_f32 v54, v54, v55
	v_cvt_pk_bf16_f32 v55, v56, v57
	ds_write_b64 v142, v[54:55]
	s_waitcnt lgkmcnt(0)
	s_barrier
	ds_read2_b64 v[54:57], v143 offset1:16
	ds_read_b128 v[184:187], v137
	v_pk_mul_f32 v[6:7], v[74:75], v[6:7]
	v_pk_mul_f32 v[4:5], v[76:77], v[4:5]
	v_lshl_add_u64 v[110:111], v[110:111], 0, s[8:9]
	s_waitcnt lgkmcnt(1)
	v_sub_f32_e32 v41, v41, v54
	v_sub_f32_e32 v40, v40, v54
	v_sub_f32_e32 v43, v43, v54
	v_sub_f32_e32 v42, v42, v54
	v_pk_mul_f32 v[42:43], v[54:55], v[42:43] op_sel:[1,0]
	v_pk_mul_f32 v[40:41], v[54:55], v[40:41] op_sel:[1,0]
	v_pk_mul_f32 v[42:43], v[2:3], v[42:43]
	v_pk_mul_f32 v[40:41], v[0:1], v[40:41]
	v_pk_mul_f32 v[42:43], v[42:43], v[188:189]
	v_pk_mul_f32 v[40:41], v[40:41], v[60:61]
	v_sub_f32_e32 v45, v45, v56
	v_cvt_pk_bf16_f32 v40, v40, v41
	v_cvt_pk_bf16_f32 v41, v42, v43
	v_sub_f32_e32 v44, v44, v56
	global_store_dwordx2 v[58:59], v[40:41], off
	v_sub_f32_e32 v41, v47, v56
	v_sub_f32_e32 v40, v46, v56
	v_pk_mul_f32 v[40:41], v[56:57], v[40:41] op_sel:[1,0]
	v_pk_mul_f32 v[42:43], v[56:57], v[44:45] op_sel:[1,0]
	ds_read2_b64 v[54:57], v143 offset0:32 offset1:48
	v_pk_mul_f32 v[42:43], v[0:1], v[42:43]
	v_pk_mul_f32 v[40:41], v[2:3], v[40:41]
	v_lshlrev_b32_e32 v44, 16, v52
	v_and_b32_e32 v45, 0xffff0000, v52
	v_lshlrev_b32_e32 v46, 16, v53
	v_and_b32_e32 v47, 0xffff0000, v53
	v_pk_mul_f32 v[40:41], v[40:41], v[46:47]
	v_pk_mul_f32 v[42:43], v[42:43], v[44:45]
	ds_read_b128 v[188:191], v137 offset:64
	v_cvt_pk_bf16_f32 v42, v42, v43
	v_cvt_pk_bf16_f32 v43, v40, v41
	v_add_co_u32_e32 v40, vcc, s67, v120
	s_nop 0
	v_addc_co_u32_e32 v41, vcc, 0, v121, vcc
	global_store_dwordx2 v[40:41], v[42:43], off
	s_waitcnt lgkmcnt(1)
	v_sub_f32_e32 v41, v49, v54
	v_sub_f32_e32 v40, v48, v54
	v_sub_f32_e32 v43, v51, v54
	v_sub_f32_e32 v42, v50, v54
	v_pk_mul_f32 v[40:41], v[54:55], v[40:41] op_sel:[1,0]
	v_pk_mul_f32 v[192:193], v[54:55], v[42:43] op_sel:[1,0]
	v_pk_mul_f32 v[196:197], v[0:1], v[40:41]
	s_waitcnt lgkmcnt(0)
	v_mfma_f32_16x16x32_bf16 v[40:43], v[184:187], v[216:219], 0
	v_add3_u32 v48, s18, v162, v168
	ds_read_b64_tr_b16 v[58:59], v48 offset:27648
	ds_read_b64_tr_b16 v[60:61], v48 offset:28800
	ds_read_b64_tr_b16 v[52:53], v48 offset:36864
	ds_read_b64_tr_b16 v[54:55], v48 offset:38016
	ds_read_b128 v[48:51], v129
	v_pk_mul_f32 v[192:193], v[2:3], v[192:193]
	v_mfma_f32_16x16x32_bf16 v[40:43], v[188:191], v[220:223], v[40:43]
	ds_read_b128 v[44:47], v129 offset:64
	v_pk_mul_f32 v[122:123], v[192:193], v[122:123]
	ds_read_b128 v[192:195], v129 offset:2304
	v_lshl_add_u64 v[112:113], v[112:113], 0, s[12:13]
	v_lshl_add_u64 v[114:115], v[114:115], 0, s[14:15]
	s_nop 2
	v_pk_mul_f32 v[42:43], v[108:109], v[42:43]
	v_pk_mul_f32 v[40:41], v[90:91], v[40:41]
	s_cmp_lg_u32 s89, 30
	v_lshl_add_u64 v[116:117], v[116:117], 0, s[12:13]
	s_waitcnt lgkmcnt(2)
	v_mfma_f32_16x16x32_bf16 v[40:43], v[58:61], v[48:51], v[40:43]
	s_waitcnt lgkmcnt(1)
	v_mfma_f32_16x16x32_bf16 v[40:43], v[52:55], v[44:47], v[40:43]
	s_waitcnt lgkmcnt(0)
	v_mfma_f32_16x16x32_bf16 v[48:51], v[184:187], v[224:227], 0
	s_waitcnt lgkmcnt(0)
	v_mfma_f32_16x16x32_bf16 v[44:47], v[188:191], v[228:231], v[48:51]
	ds_read_b64_tr_b16 v[216:217], v212 offset:18432
	ds_read_b64_tr_b16 v[218:219], v212 offset:19008
	ds_read_b64_tr_b16 v[220:221], v212 offset:23040
	ds_read_b64_tr_b16 v[222:223], v212 offset:23616
	ds_read_b64_tr_b16 v[224:225], v212 offset:18464
	ds_read_b64_tr_b16 v[226:227], v212 offset:19040
	ds_read_b64_tr_b16 v[228:229], v212 offset:23072
	ds_read_b64_tr_b16 v[230:231], v212 offset:23648
	s_nop 5
	ds_read_b128 v[48:51], v129 offset:2368
	s_nop 0
	v_pk_mul_f32 v[46:47], v[106:107], v[46:47]
	v_pk_mul_f32 v[44:45], v[78:79], v[44:45]
	s_nop 1
	v_mfma_f32_16x16x32_bf16 v[44:47], v[58:61], v[192:195], v[44:47]
	v_mul_f32_e64 v192, v196, v200
	v_mul_f32_e64 v193, v197, v201
	ds_read_b128 v[200:203], v129 offset:4608
	v_cvt_pk_bf16_f32 v192, v192, v193
	s_waitcnt lgkmcnt(1)
; #define LAS __attribute__((address_space(3)))
; __device__ __forceinline__ unsigned pk2(float lo, float hi) { return pg8::cvt_pk_bf16(lo, hi); }
; __device__ __forceinline__ f32x4 mfma16(bf16x8 a, bf16x8 b, f32x4 c) { return __builtin_amdgcn_mfma_f32_16x16x32_bf16(a, b, c, 0, 0, 0); }
; __device__ __forceinline__ void retention_unit(LAS unsigned char* lds, const Ptrs& P, int b, int h, int tid) {
;     ...
;         if (n < 32) {
;             f32x4 o[4]; bf16x8 bst[2], bv[2];
; #pragma unroll
;             for (int ks = 0; ks < 2; ++ks) { bst[ks] = *(const LAS bf16x8*)(St + (16 * w + fr) * S72 + 32 * ks + 8 * fq); bv[ks] = tr_frag(bufc + ROFF_V, S144 * 2, w, ks, fq, fr); }
; #pragma unroll
;             for (int it = 0; it < 4; ++it) { o[it] = (f32x4){0.f, 0.f, 0.f, 0.f};
; #pragma unroll
;                 for (int ks = 0; ks < 2; ++ks) { const bf16x8 qf = *(const LAS bf16x8*)(Qs + (16 * it + fr) * S72 + 32 * ks + 8 * fq); o[it] = mfma16(bst[ks], qf, o[it]); }
;                 o[it] = o[it] * dqv[it];
; #pragma unroll
;                 for (int ks = 0; ks < 2; ++ks) { const bf16x8 sf = *(const LAS bf16x8*)(Ss + (16 * it + fr) * S72 + 32 * ks + 8 * fq); o[it] = mfma16(bv[ks], sf, o[it]); }
;             }
; #pragma unroll
;             for (int dt = 0; dt < 4; ++dt) { st[dt] = st[dt] * dch;
; #pragma unroll
;                 for (int ks = 0; ks < 2; ++ks) { const bf16x8 kf = tr_frag(bufc + ROFF_K2, S72 * 2, dt, ks, fq, fr); st[dt] = mfma16(kf, bv[ks], st[dt]); }
;                 v2u pw; pw.x = pk2(st[dt][0], st[dt][1]); pw.y = pk2(st[dt][2], st[dt][3]);
;                 *(LAS v2u*)(St + (16 * w + fr) * S72 + 16 * dt + 4 * fq) = pw; }
; #pragma unroll
;             for (int it = 0; it < 4; ++it) { const f32x4 v = o[it]; typedef float f32x2 __attribute__((ext_vector_type(2)));
;                 *(LAS f32x2*)(part + ((16 * it + fr) * 32 + w * 4 + fq) * 2) = (f32x2){(v[0] + v[1]) + (v[2] + v[3]), (v[0] * v[0] + v[1] * v[1]) + (v[2] * v[2] + v[3] * v[3])};
;                 op[it] = v; }
	v_mfma_f32_16x16x32_bf16 v[44:47], v[52:55], v[48:51], v[44:47]
	v_cvt_pk_bf16_f32 v193, v122, v123
	v_add_co_u32_e32 v122, vcc, s68, v120
	v_sub_f32_e32 v197, v23, v56
	s_nop 0
	v_addc_co_u32_e32 v123, vcc, 0, v121, vcc
	global_store_dwordx2 v[122:123], v[192:193], off
	s_waitcnt lgkmcnt(0)
	v_mfma_f32_16x16x32_bf16 v[48:51], v[184:187], v[232:235], 0
	v_sub_f32_e32 v123, v21, v56
	v_sub_f32_e32 v122, v20, v56
	v_sub_f32_e32 v196, v22, v56
	s_waitcnt lgkmcnt(0)
	v_mfma_f32_16x16x32_bf16 v[48:51], v[188:191], v[236:239], v[48:51]
	ds_read_b64_tr_b16 v[232:233], v212 offset:18496
	ds_read_b64_tr_b16 v[234:235], v212 offset:19072
	ds_read_b64_tr_b16 v[236:237], v212 offset:23104
	ds_read_b64_tr_b16 v[238:239], v212 offset:23680
	ds_read_b128 v[192:195], v129 offset:4672
	v_pk_mul_f32 v[196:197], v[56:57], v[196:197] op_sel:[1,0]
	v_pk_mul_f32 v[56:57], v[56:57], v[122:123] op_sel:[1,0]
	v_pk_mul_f32 v[122:123], v[2:3], v[196:197]
	v_pk_mul_f32 v[56:57], v[0:1], v[56:57]
	s_nop 2
	v_pk_mul_f32 v[50:51], v[104:105], v[50:51]
	v_pk_mul_f32 v[48:49], v[86:87], v[48:49]
	s_waitcnt vmcnt(7)
	v_lshlrev_b32_e32 v196, 16, v118
	v_and_b32_e32 v197, 0xffff0000, v118
	v_mfma_f32_16x16x32_bf16 v[48:51], v[58:61], v[200:203], v[48:51]
	s_waitcnt lgkmcnt(0)
	v_mfma_f32_16x16x32_bf16 v[16:19], v[216:219], v[58:61], v[16:19]
	s_waitcnt lgkmcnt(0)
	v_mfma_f32_16x16x32_bf16 v[16:19], v[220:223], v[52:55], v[16:19]
	v_mfma_f32_16x16x32_bf16 v[48:51], v[52:55], v[192:195], v[48:51]
	ds_read_b128 v[204:207], v129 offset:6912
	ds_read_b128 v[208:211], v129 offset:6976
	s_nop 2
	v_cvt_pk_bf16_f32 v20, v16, v17
	v_cvt_pk_bf16_f32 v21, v18, v19
	ds_write_b64 v132, v[20:21]
	s_waitcnt lgkmcnt(3)
	v_mfma_f32_16x16x32_bf16 v[184:187], v[184:187], v[240:243], 0
	s_waitcnt lgkmcnt(0)
	v_mfma_f32_16x16x32_bf16 v[12:15], v[224:227], v[58:61], v[12:15]
	s_waitcnt lgkmcnt(0)
	v_mfma_f32_16x16x32_bf16 v[12:15], v[228:231], v[52:55], v[12:15]
	v_mfma_f32_16x16x32_bf16 v[184:187], v[188:191], v[244:247], v[184:187]
	ds_read_b64_tr_b16 v[240:241], v212 offset:18528
	ds_read_b64_tr_b16 v[242:243], v212 offset:19104
	ds_read_b64_tr_b16 v[244:245], v212 offset:23136
	ds_read_b64_tr_b16 v[246:247], v212 offset:23712
	s_nop 6
	v_cvt_pk_bf16_f32 v20, v12, v13
	v_cvt_pk_bf16_f32 v21, v14, v15
	ds_write_b64 v132, v[20:21] offset:32
	s_waitcnt lgkmcnt(0)
	v_mfma_f32_16x16x32_bf16 v[8:11], v[232:235], v[58:61], v[8:11]
	v_mul_f32_e64 v186, v96, v186
	v_mul_f32_e64 v187, v97, v187
	v_pk_mul_f32 v[184:185], v[88:89], v[184:185]
	v_lshlrev_b32_e32 v20, 16, v119
	s_waitcnt lgkmcnt(0)
	v_mfma_f32_16x16x32_bf16 v[8:11], v[236:239], v[52:55], v[8:11]
	v_and_b32_e32 v21, 0xffff0000, v119
	v_pk_mul_f32 v[20:21], v[122:123], v[20:21]
	v_mfma_f32_16x16x32_bf16 v[184:187], v[58:61], v[204:207], v[184:187]
	s_nop 4
	v_cvt_pk_bf16_f32 v22, v8, v9
	v_cvt_pk_bf16_f32 v23, v10, v11
	ds_write_b64 v132, v[22:23] offset:64
	v_pk_mul_f32 v[22:23], v[56:57], v[196:197]
	v_cvt_pk_bf16_f32 v57, v20, v21
	v_cvt_pk_bf16_f32 v56, v22, v23
	v_mfma_f32_16x16x32_bf16 v[20:23], v[52:55], v[208:211], v[184:187]
	s_nop 2
	s_waitcnt lgkmcnt(0)
	v_mfma_f32_16x16x32_bf16 v[4:7], v[240:243], v[58:61], v[4:7]
	v_add_co_u32_e32 v58, vcc, s69, v120
	s_waitcnt lgkmcnt(0)
	v_mfma_f32_16x16x32_bf16 v[4:7], v[244:247], v[52:55], v[4:7]
	v_addc_co_u32_e32 v59, vcc, 0, v121, vcc
	global_store_dwordx2 v[58:59], v[56:57], off
	v_mul_f32_e32 v55, v41, v41
	v_mul_f32_e32 v57, v42, v42
	s_nop 3
	v_cvt_pk_bf16_f32 v52, v4, v5
	v_cvt_pk_bf16_f32 v53, v6, v7
	ds_write_b64 v132, v[52:53] offset:96
	v_mul_f32_e32 v53, v40, v40
	v_mul_f32_e32 v59, v43, v43
	v_mov_b32_e32 v52, v40
	v_mov_b32_e32 v54, v41
	v_mov_b32_e32 v56, v42
	v_mov_b32_e32 v58, v43
	v_pk_add_f32 v[52:53], v[52:53], v[54:55]
	v_pk_add_f32 v[54:55], v[56:57], v[58:59]
	v_mul_f32_e32 v57, v46, v46
	v_pk_add_f32 v[52:53], v[52:53], v[54:55]
	ds_write_b64 v133, v[52:53]
	v_mul_f32_e32 v53, v44, v44
	v_mul_f32_e32 v55, v45, v45
	v_mul_f32_e32 v59, v47, v47
	v_mov_b32_e32 v52, v44
	v_mov_b32_e32 v54, v45
	v_mov_b32_e32 v56, v46
	v_mov_b32_e32 v58, v47
	v_pk_add_f32 v[52:53], v[52:53], v[54:55]
	v_pk_add_f32 v[54:55], v[56:57], v[58:59]
	v_mul_f32_e32 v57, v50, v50
	v_pk_add_f32 v[52:53], v[52:53], v[54:55]
	ds_write_b64 v134, v[52:53]
	v_mul_f32_e32 v53, v48, v48
	v_mul_f32_e32 v55, v49, v49
	v_mul_f32_e32 v59, v51, v51
	v_mov_b32_e32 v52, v48
	v_mov_b32_e32 v54, v49
	v_mov_b32_e32 v56, v50
	v_mov_b32_e32 v58, v51
	v_pk_add_f32 v[52:53], v[52:53], v[54:55]
	v_pk_add_f32 v[54:55], v[56:57], v[58:59]
	v_mul_f32_e32 v57, v22, v22
	v_pk_add_f32 v[52:53], v[52:53], v[54:55]
	ds_write_b64 v135, v[52:53]
	v_mul_f32_e32 v53, v20, v20
	v_mul_f32_e32 v55, v21, v21
	v_mul_f32_e32 v59, v23, v23
	v_mov_b32_e32 v52, v20
	v_mov_b32_e32 v54, v21
	v_mov_b32_e32 v56, v22
	v_mov_b32_e32 v58, v23
	v_pk_add_f32 v[52:53], v[52:53], v[54:55]
	v_pk_add_f32 v[54:55], v[56:57], v[58:59]
	s_nop 0
	v_pk_add_f32 v[52:53], v[52:53], v[54:55]
	ds_write_b64 v136, v[52:53]
	s_cbranch_scc0 .LBB0_660
; #define LAS __attribute__((address_space(3)))
; #define LBAR() do { asm volatile("s_waitcnt lgkmcnt(0)" ::: "memory"); __builtin_amdgcn_s_barrier(); asm volatile("" ::: "memory"); } while (0)
; __device__ __forceinline__ unsigned pk2(float lo, float hi) { return pg8::cvt_pk_bf16(lo, hi); }
; __device__ __forceinline__ void retention_unit(LAS unsigned char* lds, const Ptrs& P, int b, int h, int tid) {
;     ...
;         LAS unsigned char* bufc = lds + (n & 1) * RSET;
;         LAS bf16* Qs = (LAS bf16*)(bufc + ROFF_Q); LAS bf16* Ks = (LAS bf16*)(bufc + ROFF_K); LAS bf16* K2s = (LAS bf16*)(bufc + ROFF_K2); LAS bf16* Vs = (LAS bf16*)(bufc + ROFF_V);
;         if (n < 32) {
;             *(LAS v4u*)(Qs + lrow * S72 + lseg * 8) = rq; *(LAS v4u*)(Ks + lrow * S72 + lseg * 8) = rk;
;             v4u k2;
; #pragma unroll
;             for (int t = 0; t < 4; ++t) k2[t] = pk2(bflo(rk[t]) * dkey, bfhi(rk[t]) * dkey);
;             *(LAS v4u*)(K2s + lrow * S72 + lseg * 8) = k2;
;             *(LAS v4u*)(Vs + vrow0 * S144 + vseg * 8) = rv0; *(LAS v4u*)(Vs + (vrow0 + 32) * S144 + vseg * 8) = rv1;
;         }
;         if (n >= 1) {
; #pragma unroll
;             for (int it = 0; it < 4; ++it) sgr[it] = __builtin_nontemporal_load((const v2u*)(gsl + ((size_t)(n - 1) * 64 + 16 * it) * 512));
;         }
;         LBAR();
;         if (n + 1 < 32) { const size_t o4 = (size_t)(n + 1) * 64;
;             rq = __builtin_nontemporal_load((const v4u*)(gq + o4 * 256)); rk = __builtin_nontemporal_load((const v4u*)(gk + o4 * 256)); rv0 = __builtin_nontemporal_load((const v4u*)(gv + o4 * 512)); rv1 = __builtin_nontemporal_load((const v4u*)(gv + (o4 + 32) * 512)); }
;         if (n >= 1) {
;             const int row = tid >> 3, sub = tid & 7;
;             const f32x4 pa = *(const LAS f32x4*)(part + (row * 32 + sub * 4) * 2), pb = *(const LAS f32x4*)(part + (row * 32 + sub * 4) * 2 + 4);
;             float s1 = (pa[0] + pa[2]) + (pb[0] + pb[2]), s2 = (pa[1] + pa[3]) + (pb[1] + pb[3]);
; #pragma unroll
;             for (int x = 1; x < 8; x <<= 1) { s1 += __shfl_xor(s1, x); s2 += __shfl_xor(s2, x); }
;             if (sub == 0) { const float mean = s1 * (1.f / 128.f); float var = s2 * (1.f / 128.f) - mean * mean; var = var < 0.f ? 0.f : var;
;                 stat[row * 2] = mean; stat[row * 2 + 1] = __builtin_amdgcn_rsqf(var + 1e-5f); }
;         }
.LBB0_658:
	s_add_i32 s89, s89, 1
	s_bitcmp1_b32 s89, 0
	s_cselect_b32 s18, 0xb400, 0
	s_add_i32 s90, s18, 0
	v_add3_u32 v52, s90, v163, v72
	s_waitcnt vmcnt(7)
	ds_write_b128 v52, v[36:39]
	s_waitcnt vmcnt(6)
	ds_write_b128 v52, v[24:27] offset:9216
	v_lshlrev_b32_e32 v36, 16, v24
	v_and_b32_e32 v37, 0xffff0000, v24
	v_pk_mul_f32 v[36:37], v[102:103], v[36:37]
	v_add_u32_e32 v56, 0, v159
	v_cvt_pk_bf16_f32 v24, v36, v37
	v_lshlrev_b32_e32 v36, 16, v25
	v_and_b32_e32 v37, 0xffff0000, v25
	v_pk_mul_f32 v[36:37], v[102:103], v[36:37]
	v_add_u32_e32 v139, 0x1d400, v56
	v_cvt_pk_bf16_f32 v25, v36, v37
	v_lshlrev_b32_e32 v36, 16, v26
	v_and_b32_e32 v37, 0xffff0000, v26
	v_pk_mul_f32 v[36:37], v[102:103], v[36:37]
	v_and_b32_e32 v60, 64, v131
	v_cvt_pk_bf16_f32 v26, v36, v37
	v_lshlrev_b32_e32 v36, 16, v27
	v_and_b32_e32 v37, 0xffff0000, v27
	v_pk_mul_f32 v[36:37], v[102:103], v[36:37]
	v_add_u32_e32 v60, 64, v60
	v_cvt_pk_bf16_f32 v27, v36, v37
	ds_write_b128 v52, v[24:27] offset:18432
	v_add3_u32 v24, s90, v158, v84
	s_waitcnt vmcnt(5)
	ds_write_b128 v24, v[28:31] offset:27648
	s_waitcnt vmcnt(4)
	ds_write_b128 v24, v[32:35] offset:36864
	v_lshl_add_u64 v[24:25], s[26:27], 0, v[116:117]
	v_add_co_u32_e32 v26, vcc, s58, v24
	v_xor_b32_e32 v61, 1, v131
	s_nop 0
	v_addc_co_u32_e32 v27, vcc, 0, v25, vcc
	v_add_co_u32_e32 v28, vcc, s59, v24
	s_nop 1
	v_addc_co_u32_e32 v29, vcc, 0, v25, vcc
	v_add_co_u32_e32 v30, vcc, s60, v24
	s_nop 1
	v_addc_co_u32_e32 v31, vcc, 0, v25, vcc
	v_add_co_u32_e32 v24, vcc, s61, v24
	s_nop 1
	v_addc_co_u32_e32 v25, vcc, 0, v25, vcc
	global_load_dwordx2 v[54:55], v[26:27], off nt
	global_load_dwordx2 v[52:53], v[28:29], off nt
	global_load_dwordx2 v[122:123], v[30:31], off nt
	global_load_dwordx2 v[118:119], v[24:25], off nt
	v_lshl_add_u64 v[24:25], s[26:27], 0, v[110:111]
	v_add_co_u32_e32 v26, vcc, s62, v24
	v_lshl_add_u64 v[28:29], s[26:27], 0, v[112:113]
	s_nop 0
	v_addc_co_u32_e32 v27, vcc, 0, v25, vcc
	v_add_co_u32_e32 v24, vcc, s63, v24
	s_waitcnt lgkmcnt(0)
	s_barrier
	v_lshl_add_u32 v213, v155, 1, s90
	v_add_u32_e32 v214, v213, v179
	v_add_u32_e32 v215, v213, v62
	ds_read_b128 v[216:219], v214 offset:9216
	ds_read_b128 v[220:223], v214 offset:9280
	ds_read_b128 v[188:191], v215
	ds_read_b128 v[192:195], v215 offset:64
	s_nop 0
	v_addc_co_u32_e32 v25, vcc, 0, v25, vcc
	v_add_co_u32_e32 v30, vcc, s64, v28
	global_load_dwordx4 v[36:39], v[26:27], off nt
	s_nop 0
	global_load_dwordx4 v[24:27], v[24:25], off nt
	v_addc_co_u32_e32 v31, vcc, 0, v29, vcc
	v_add_co_u32_e32 v32, vcc, s65, v28
	s_nop 1
	v_addc_co_u32_e32 v33, vcc, 0, v29, vcc
	global_load_dwordx4 v[28:31], v[30:31], off nt
	s_nop 0
	global_load_dwordx4 v[32:35], v[32:33], off nt
	ds_read_b128 v[56:59], v139
	ds_read_b128 v[184:187], v139 offset:16
	v_cmp_lt_i32_e32 vcc, v61, v60
	s_waitcnt lgkmcnt(1)
	v_pk_add_f32 v[56:57], v[56:57], v[58:59]
	v_cndmask_b32_e32 v61, v131, v61, vcc
	s_waitcnt lgkmcnt(0)
	v_pk_add_f32 v[58:59], v[184:185], v[186:187]
	v_lshlrev_b32_e32 v138, 2, v61
	v_pk_add_f32 v[56:57], v[56:57], v[58:59]
	s_nop 1
	v_add_f32_dpp v56, v56, v56 quad_perm:[1,0,3,2] row_mask:0xf bank_mask:0xf
	v_add_f32_dpp v57, v57, v57 quad_perm:[1,0,3,2] row_mask:0xf bank_mask:0xf
	v_xor_b32_e32 v61, 2, v131
	v_cmp_lt_i32_e32 vcc, v61, v60
	s_nop 1
	v_cndmask_b32_e32 v61, v131, v61, vcc
	v_lshlrev_b32_e32 v140, 2, v61
	v_add_f32_dpp v56, v56, v56 quad_perm:[2,3,0,1] row_mask:0xf bank_mask:0xf
	v_add_f32_dpp v57, v57, v57 quad_perm:[2,3,0,1] row_mask:0xf bank_mask:0xf
	v_xor_b32_e32 v58, 4, v131
	v_cmp_lt_i32_e32 vcc, v58, v60
	s_nop 1
	v_cndmask_b32_e32 v58, v131, v58, vcc
	v_lshlrev_b32_e32 v141, 2, v58
	v_add_f32_dpp v56, v56, v56 row_half_mirror row_mask:0xf bank_mask:0xf
	v_add_f32_dpp v57, v57, v57 row_half_mirror row_mask:0xf bank_mask:0xf
	s_and_saveexec_b64 s[18:19], s[0:1]
	s_cbranch_execz .LBB0_657
	s_waitcnt lgkmcnt(0)
	v_add_u32_e32 v58, 0, v198
	v_pk_mul_f32 v[56:57], v[56:57], s[6:7] op_sel_hi:[1,0]
	v_add_u32_e32 v58, 0x21400, v58
	v_fma_f32 v57, -v56, v56, v57
	v_cmp_ngt_f32_e32 vcc, 0, v57
	s_nop 1
	v_cndmask_b32_e32 v57, 0, v57, vcc
	v_add_f32_e32 v57, 0x3727c5ac, v57
	v_rsq_f32_e32 v57, v57
	ds_write2_b32 v58, v56, v57 offset1:1
	s_branch .LBB0_657
